# attention: row reference max snapped to 0 when within +-8; tiles whose rows all have reference 0 skip the 32 S-m subtractions (general path otherwise)
# baseline (speedup 1.0000x reference)
.LBB0_189:
	s_cmp_gt_i32 s27, 1
	s_mov_b64 s[6:7], -1
	s_cbranch_scc0 .LBB0_345
	s_cmp_gt_i32 s27, 2
	s_cbranch_scc0 .LBB0_233
	s_cmp_lt_i32 s94, 19
	s_cbranch_scc1 .LBB0_232
	v_writelane_b32 v255, s27, 36
	s_mov_b32 s4, s18
	v_writelane_b32 v255, s4, 34
	s_add_i32 s8, s18, -2
	v_bfe_u32 v198, v168, 5, 1
	v_writelane_b32 v255, s5, 35
	s_lshl_b32 s4, s8, 1
	s_lshl_b64 s[6:7], s[4:5], 2
	s_add_u32 s6, s88, s6
	s_addc_u32 s7, s89, s7
	global_load_dwordx2 v[170:171], v161, s[6:7] offset:64
	s_lshl_b32 s4, s8, 4
	s_lshl_b64 s[6:7], s[4:5], 2
	s_add_u32 s6, s88, s6
	s_addc_u32 s7, s89, s7
	v_writelane_b32 v255, s6, 37
	v_readlane_b32 s4, v253, 14
	v_readlane_b32 s12, v252, 19
	v_writelane_b32 v255, s7, 38
	v_ashrrev_i32_e32 v200, 4, v166
	v_readlane_b32 s6, v255, 29
	s_cmp_lt_i32 s6, s4
	s_cselect_b64 s[84:85], -1, 0
	s_cmp_ge_i32 s6, s4
	s_cselect_b64 s[6:7], -1, 0
	s_lshl_b32 s4, s8, 7
	s_lshl_b64 s[8:9], s[4:5], 2
	v_and_b32_e32 v4, 15, v168
	v_lshlrev_b32_e32 v5, 4, v168
	v_readlane_b32 s10, v252, 42
	s_movk_i32 s4, 0x110
	v_lshlrev_b32_e32 v160, 4, v198
	v_readlane_b32 s22, v252, 29
	s_waitcnt lgkmcnt(0)
	v_and_b32_e32 v1, 63, v168
	v_ashrrev_i32_e32 v2, 8, v166
	v_lshlrev_b32_e32 v0, 3, v4
	v_and_b32_e32 v174, 0x70, v5
	v_mov_b32_e32 v175, v161
	v_readlane_b32 s11, v252, 43
	v_lshlrev_b32_e32 v4, 4, v4
	v_mul_lo_u32 v6, v200, s4
	v_lshlrev_b32_e32 v201, 3, v168
	v_add_u32_e32 v202, 0, v160
	v_xor_b32_e32 v8, 32, v220
	v_readlane_b32 s20, v252, 27
	v_readlane_b32 s21, v252, 28
	v_readlane_b32 s23, v252, 30
	s_add_u32 s8, s22, s8
	v_and_b32_e32 v181, 31, v168
	v_bfe_u32 v3, v166, 6, 2
	v_lshlrev_b32_e32 v176, 6, v2
	v_ashrrev_i32_e32 v178, 3, v166
	v_lshl_add_u64 v[182:183], s[10:11], 0, v[174:175]
	v_add3_u32 v175, 0, v4, v6
	v_and_b32_e32 v4, 0x60, v5
	v_and_b32_e32 v5, 8, v201
	s_movk_i32 s4, 0x90
	v_lshl_add_u32 v203, v2, 7, v202
	v_readlane_b32 s10, v254, 41
	v_mov_b32_e32 v7, 0x3600
	v_cmp_lt_i32_e32 vcc, v8, v221
	v_cmp_eq_u32_e64 s[38:39], 1, v2
	v_lshl_add_u32 v1, v1, 2, 0
	v_lshlrev_b32_e32 v2, 8, v166
	v_readlane_b32 s20, v255, 17
	s_addc_u32 s9, s23, s9
	v_lshlrev_b32_e32 v199, 5, v3
	v_lshlrev_b32_e32 v172, 3, v198
	v_add3_u32 v6, 0, v4, v5
	v_mul_lo_u32 v167, v178, s4
	v_add3_u32 v4, s10, v4, v5
	v_add_u32_e32 v5, s10, v160
	v_mul_u32_u24_e32 v169, 0x90, v181
	v_mad_u32_u24 v7, v181, s4, v7
	v_cndmask_b32_e32 v8, v220, v8, vcc
	v_lshl_add_u32 v205, v3, 14, v1
	s_movk_i32 s4, 0x100
	v_and_b32_e32 v3, 0xc000, v2
	v_or_b32_e32 v2, 0x3f00, v2
	v_cmp_eq_u32_e64 s[36:37], 0, v166
	v_readlane_b32 s21, v255, 18
	v_ashrrev_i32_e32 v177, 31, v176
	v_ashrrev_i32_e32 v179, 31, v178
	v_mul_u32_u24_e32 v204, 0x110, v181
	v_lshlrev_b32_e32 v180, 2, v198
	v_lshlrev_b32_e32 v173, 2, v8
	v_cmp_gt_u32_e64 s[40:41], s4, v166
	v_add_u32_e32 v206, v1, v3
	v_lshl_add_u64 v[184:185], s[8:9], 0, v[160:161]
	s_mov_b64 s[8:9], -1
	s_waitcnt vmcnt(0)
	v_mov_b32_e32 v186, v170
	v_mov_b32_e32 v187, v170
	v_add_u32_e32 v207, v202, v7
	v_add_u32_e32 v208, v4, v167
	v_add_u32_e32 v209, v5, v169
	v_add_u32_e32 v210, v1, v2
	v_lshlrev_b32_e32 v188, 1, v172
	v_lshlrev_b32_e32 v190, 1, v0
	v_add_u32_e32 v211, v6, v167
	v_readlane_b32 s13, v252, 20
	v_readlane_b32 s14, v252, 21
	v_readlane_b32 s15, v252, 22
	v_readlane_b32 s16, v252, 23
	v_readlane_b32 s17, v252, 24
	v_readlane_b32 s18, v252, 25
	v_readlane_b32 s19, v252, 26
	v_readlane_b32 s24, v252, 31
	v_readlane_b32 s25, v252, 32
	v_readlane_b32 s26, v252, 33
	v_readlane_b32 s27, v252, 34
	s_mov_b32 s98, 0x41000000
	s_branch .LBB0_194

.LBB0_201:
	s_or_b64 exec, exec, s[6:7]
	v_mov_b32_e32 v0, s97
	s_waitcnt lgkmcnt(0)
	s_barrier
	ds_read_b32 v0, v0
	s_movk_i32 s6, 0x17f
	s_waitcnt lgkmcnt(0)
	s_barrier
	v_cmp_lt_u32_e32 vcc, s6, v0
	v_readfirstlane_b32 s4, v0
	s_mov_b64 s[6:7], -1
	s_cbranch_vccnz .LBB0_196
	s_add_i32 s4, s4, s26
	s_and_b32 s6, s4, 0xffff
	s_mul_i32 s6, s6, 0xaaab
	s_lshr_b32 s8, s6, 20
	s_mul_i32 s6, s8, 24
	s_sub_i32 s9, s4, s6
	s_mul_i32 s4, s9, 0xab
	s_lshl_b32 s7, s8, 7
	s_bfe_u32 s4, s4, 0x6000a
	v_subrev_u32_e32 v26, s7, v199
	s_mul_i32 s6, s4, 6
	v_add_u32_e32 v212, 0xf80, v26
	s_sub_i32 s6, s9, s6
	v_or_b32_e32 v213, v212, v181
	s_lshl_b32 s7, s4, 12
	v_add_lshl_u32 v160, v213, s7, 11
	s_and_b32 s10, s6, 0xff
	v_lshl_add_u64 v[0:1], s[64:65], 0, v[160:161]
	s_lshl_b32 s4, s10, 8
	v_lshl_add_u64 v[0:1], v[0:1], 0, s[4:5]
	v_lshl_add_u64 v[0:1], v[176:177], 1, v[0:1]
	v_mov_b32_e32 v189, v161
	v_lshl_add_u64 v[24:25], v[0:1], 0, v[188:189]
	v_add_u32_e32 v2, s7, v200
	v_mov_b64_e32 v[0:1], s[30:31]
	v_mad_i64_i32 v[0:1], s[6:7], v2, s35, v[0:1]
	v_lshl_add_u64 v[0:1], v[0:1], 0, s[4:5]
	s_lshl_b32 s4, s9, 7
	v_mov_b32_e32 v191, v161
	s_and_b32 s4, s4, 0xff80
	v_lshl_add_u64 v[194:195], v[0:1], 0, v[190:191]
	v_lshl_add_u64 v[0:1], s[4:5], 0, v[178:179]
	s_mov_b32 s4, 0xc000
	v_lshlrev_b64 v[0:1], 13, v[0:1]
	v_add_co_u32_e32 v8, vcc, s4, v194
	v_lshl_add_u64 v[196:197], v[182:183], 0, v[0:1]
	s_nop 0
	v_addc_co_u32_e32 v9, vcc, 0, v195, vcc
	s_mov_b32 s4, 0x80000
	v_add_co_u32_e32 v12, vcc, s4, v196
	s_mov_b32 s4, 0x18000
	s_nop 0
	v_addc_co_u32_e32 v13, vcc, 0, v197, vcc
	global_load_dwordx4 v[0:3], v[194:195], off
	global_load_dwordx4 v[4:7], v[196:197], off
	s_nop 0
	global_load_dwordx4 v[8:11], v[8:9], off
	s_nop 0
	global_load_dwordx4 v[12:15], v[12:13], off
	v_add_co_u32_e32 v16, vcc, s4, v194
	s_mov_b32 s4, 0x24000
	s_nop 0
	v_addc_co_u32_e32 v17, vcc, 0, v195, vcc
	v_add_co_u32_e32 v20, vcc, s4, v194
	s_mov_b32 s24, 1
	s_nop 0
	v_addc_co_u32_e32 v21, vcc, 0, v195, vcc
	global_load_dwordx4 v[16:19], v[16:17], off
	s_nop 0
	global_load_dwordx4 v[20:23], v[20:21], off
	s_nop 0
	global_load_dwordx4 v[128:131], v[24:25], off
	global_load_dwordx4 v[132:135], v[24:25], off offset:32
	global_load_dwordx4 v[136:139], v[24:25], off offset:64
	global_load_dwordx4 v[140:143], v[24:25], off offset:96
	v_add_u32_e32 v189, 0xc800, v211
	v_add_u32_e32 v191, 0xf000, v211
	s_lshl_b32 s27, s10, 7
	s_lshl_b32 s22, s8, 1
	s_waitcnt vmcnt(9)
	ds_write_b128 v175, v[0:3]
	s_waitcnt vmcnt(7)
	ds_write_b128 v175, v[8:11] offset:8704
	ds_write2_b64 v189, v[4:5], v[6:7] offset0:128 offset1:130
	s_waitcnt vmcnt(6)
	ds_write2_b64 v191, v[12:13], v[14:15] offset1:2
	s_waitcnt vmcnt(5)
	ds_write_b128 v175, v[16:19] offset:17408
	s_waitcnt vmcnt(4)
	ds_write_b128 v175, v[20:23] offset:26112
	s_waitcnt lgkmcnt(0)
	s_barrier
	s_setprio 1
	v_add_u32_e32 v8, v203, v204
	ds_read_b128 v[0:3], v8
	ds_read_b128 v[4:7], v8 offset:32
	s_mov_b32 s4, s5
	s_mov_b32 s6, s5
	s_mov_b32 s7, s5
	s_waitcnt vmcnt(3) lgkmcnt(1)
	v_mfma_f32_32x32x16_bf16 v[64:79], v[0:3], v[128:131], 0
	s_mov_b32 s8, s5
	s_mov_b32 s9, s5
	s_mov_b32 s10, s5
	s_mov_b32 s11, s5
	s_mov_b32 s12, s5
	s_mov_b32 s13, s5
	s_mov_b32 s14, s5
	s_waitcnt vmcnt(2) lgkmcnt(0)
	v_mfma_f32_32x32x16_bf16 v[64:79], v[4:7], v[132:135], v[64:79]
	ds_read_b128 v[0:3], v8 offset:64
	ds_read_b128 v[4:7], v8 offset:96
	s_mov_b32 s15, s5
	s_mov_b32 s16, s5
	s_mov_b32 s17, s5
	s_mov_b32 s18, s5
	s_mov_b32 s19, s5
	s_waitcnt vmcnt(1) lgkmcnt(1)
	v_mfma_f32_32x32x16_bf16 v[64:79], v[0:3], v[136:139], v[64:79]
	s_waitcnt vmcnt(0) lgkmcnt(0)
	v_mfma_f32_32x32x16_bf16 v[64:79], v[4:7], v[140:143], v[64:79]
	ds_read_b128 v[0:3], v8 offset:8704
	ds_read_b128 v[4:7], v8 offset:8736
	ds_read_b128 v[16:19], v8 offset:8800
	s_waitcnt lgkmcnt(2)
	v_mfma_f32_32x32x16_bf16 v[80:95], v[0:3], v[128:131], 0
	ds_read_b128 v[0:3], v8 offset:8768
	s_waitcnt lgkmcnt(2)
	v_mfma_f32_32x32x16_bf16 v[80:95], v[4:7], v[132:135], v[80:95]
	s_waitcnt lgkmcnt(0)
	v_mfma_f32_32x32x16_bf16 v[80:95], v[0:3], v[136:139], v[80:95]
	v_mov_b64_e32 v[0:1], s[4:5]
	v_mov_b64_e32 v[2:3], s[6:7]
	v_mov_b64_e32 v[4:5], s[8:9]
	v_mov_b64_e32 v[6:7], s[10:11]
	v_mov_b64_e32 v[8:9], s[12:13]
	v_mov_b64_e32 v[10:11], s[14:15]
	v_mov_b64_e32 v[12:13], s[16:17]
	v_mfma_f32_32x32x16_bf16 v[80:95], v[16:19], v[140:143], v[80:95]
	v_mov_b64_e32 v[14:15], s[18:19]
	s_sub_i32 s12, 64, s22
	s_setprio 0
	v_add_u32_e32 v214, 0xf9f, v26
	v_mov_b64_e32 v[30:31], v[14:15]
	v_mov_b64_e32 v[46:47], v[14:15]
	v_mov_b64_e32 v[62:63], v[14:15]
	s_mov_b32 s13, 63
	s_sub_i32 s14, 63, s22
	s_mov_b32 s16, 2
	v_mov_b32_e32 v170, 0xff800000
	s_mov_b64 s[100:101], 0
	v_mov_b32_e32 v215, 0
	s_mov_b32 s15, 3
	v_mov_b64_e32 v[28:29], v[12:13]
	v_mov_b64_e32 v[26:27], v[10:11]
	v_mov_b64_e32 v[24:25], v[8:9]
	v_mov_b64_e32 v[22:23], v[6:7]
	v_mov_b64_e32 v[20:21], v[4:5]
	v_mov_b64_e32 v[18:19], v[2:3]
	v_mov_b64_e32 v[16:17], v[0:1]
	v_mov_b64_e32 v[44:45], v[12:13]
	v_mov_b64_e32 v[42:43], v[10:11]
	v_mov_b64_e32 v[40:41], v[8:9]
	v_mov_b64_e32 v[38:39], v[6:7]
	v_mov_b64_e32 v[36:37], v[4:5]
	v_mov_b64_e32 v[34:35], v[2:3]
	v_mov_b64_e32 v[32:33], v[0:1]
	v_mov_b64_e32 v[60:61], v[12:13]
	v_mov_b64_e32 v[58:59], v[10:11]
	v_mov_b64_e32 v[56:57], v[8:9]
	v_mov_b64_e32 v[54:55], v[6:7]
	v_mov_b64_e32 v[52:53], v[4:5]
	v_mov_b64_e32 v[50:51], v[2:3]
	v_mov_b64_e32 v[48:49], v[0:1]
	s_branch .LBB0_205
.LBB0_203:
	s_cmp_eq_u64 s[100:101], 0
	s_cbranch_scc1 .Lda_nosub0
	v_sub_f32_e32 v103, v103, v234
	v_sub_f32_e32 v102, v102, v234
	v_sub_f32_e32 v101, v101, v234
	v_sub_f32_e32 v100, v100, v234
	v_sub_f32_e32 v99, v99, v234
	v_sub_f32_e32 v98, v98, v234
	v_sub_f32_e32 v97, v97, v234
	v_sub_f32_e32 v96, v96, v234
	v_sub_f32_e32 v119, v119, v234
	v_sub_f32_e32 v118, v118, v234
	v_sub_f32_e32 v117, v117, v234
	v_sub_f32_e32 v116, v116, v234
	v_sub_f32_e32 v115, v115, v234
	v_sub_f32_e32 v114, v114, v234
	v_sub_f32_e32 v113, v113, v234
	v_sub_f32_e32 v112, v112, v234
	v_sub_f32_e32 v107, v107, v234
	v_sub_f32_e32 v106, v106, v234
	v_sub_f32_e32 v105, v105, v234
	v_sub_f32_e32 v104, v104, v234
	v_sub_f32_e32 v123, v123, v234
	v_sub_f32_e32 v122, v122, v234
	v_sub_f32_e32 v121, v121, v234
	v_sub_f32_e32 v120, v120, v234
	v_sub_f32_e32 v111, v111, v234
	v_sub_f32_e32 v110, v110, v234
	v_sub_f32_e32 v109, v109, v234
	v_sub_f32_e32 v108, v108, v234
	v_sub_f32_e32 v127, v127, v234
	v_sub_f32_e32 v126, v126, v234
	v_sub_f32_e32 v125, v125, v234
	v_sub_f32_e32 v124, v124, v234
.Lda_nosub0:
	v_exp_f32_e32 v96, v96
	v_exp_f32_e32 v97, v97
	v_exp_f32_e32 v98, v98
	v_exp_f32_e32 v99, v99
	v_exp_f32_e32 v100, v100
	v_exp_f32_e32 v101, v101
	v_exp_f32_e32 v102, v102
	v_exp_f32_e32 v103, v103
	v_exp_f32_e32 v112, v112
	v_exp_f32_e32 v113, v113
	v_exp_f32_e32 v114, v114
	v_exp_f32_e32 v115, v115
	v_exp_f32_e32 v116, v116
	v_exp_f32_e32 v117, v117
	v_exp_f32_e32 v118, v118
	v_exp_f32_e32 v119, v119
	v_exp_f32_e32 v104, v104
	v_exp_f32_e32 v105, v105
	v_exp_f32_e32 v106, v106
	v_exp_f32_e32 v107, v107
	v_exp_f32_e32 v120, v120
	v_exp_f32_e32 v122, v122
	v_exp_f32_e32 v123, v123
	v_exp_f32_e32 v121, v121
	v_exp_f32_e32 v108, v108
	v_exp_f32_e32 v109, v109
	v_exp_f32_e32 v110, v110
	v_exp_f32_e32 v111, v111
	v_exp_f32_e32 v124, v124
	v_exp_f32_e32 v125, v125
	v_exp_f32_e32 v126, v126
	v_exp_f32_e32 v127, v127
	v_pk_add_f32 v[226:227], v[100:101], v[116:117]
	v_pk_add_f32 v[236:237], v[96:97], v[112:113]
	v_pk_add_f32 v[238:239], v[102:103], v[118:119]
	v_pk_add_f32 v[240:241], v[98:99], v[114:115]
	v_pk_add_f32 v[222:223], v[106:107], v[122:123]
	v_pk_add_f32 v[224:225], v[104:105], v[120:121]
	v_pk_add_f32 v[238:239], v[240:241], v[238:239]
	v_pk_add_f32 v[226:227], v[236:237], v[226:227]
	v_pk_add_f32 v[162:163], v[108:109], v[124:125]
	v_pk_add_f32 v[164:165], v[110:111], v[126:127]
	v_pk_add_f32 v[224:225], v[224:225], v[226:227]
	v_pk_add_f32 v[222:223], v[222:223], v[238:239]
	v_pk_add_f32 v[162:163], v[162:163], v[224:225]
	v_pk_add_f32 v[164:165], v[164:165], v[222:223]
	v_add_f32_e32 v162, v162, v163
	v_add_f32_e32 v163, v164, v165
	v_add_f32_e32 v162, v162, v163
	v_fmac_f32_e32 v162, v215, v170
	s_setprio 1
	ds_read_b128 v[222:225], v209
	ds_read_b128 v[240:243], v209 offset:4608
	ds_read_b128 v[244:247], v209 offset:9216
	ds_read_b128 v[248:251], v209 offset:13824
	v_cvt_pk_bf16_f32 v236, v96, v97
	v_cvt_pk_bf16_f32 v237, v98, v99
	v_cvt_pk_bf16_f32 v238, v100, v101
	v_cvt_pk_bf16_f32 v239, v102, v103
	s_waitcnt lgkmcnt(3)
	s_nop 0
	v_mfma_f32_32x32x16_bf16 v[48:63], v[222:225], v[236:239], v[48:63]
	ds_read_b128 v[222:225], v209 offset:32
	s_waitcnt lgkmcnt(3)
	v_mfma_f32_32x32x16_bf16 v[32:47], v[240:243], v[236:239], v[32:47]
	ds_read_b128 v[240:243], v209 offset:4640
	s_waitcnt lgkmcnt(3)
	v_mfma_f32_32x32x16_bf16 v[16:31], v[244:247], v[236:239], v[16:31]
	ds_read_b128 v[244:247], v209 offset:9248
	s_waitcnt lgkmcnt(3)
	v_mfma_f32_32x32x16_bf16 v[0:15], v[248:251], v[236:239], v[0:15]
	ds_read_b128 v[248:251], v209 offset:13856
	v_cvt_pk_bf16_f32 v236, v104, v105
	v_cvt_pk_bf16_f32 v237, v106, v107
	v_cvt_pk_bf16_f32 v238, v108, v109
	v_cvt_pk_bf16_f32 v239, v110, v111
	s_waitcnt lgkmcnt(3)
	s_nop 0
	v_mfma_f32_32x32x16_bf16 v[48:63], v[222:225], v[236:239], v[48:63]
	ds_read_b128 v[222:225], v209 offset:64
	s_waitcnt lgkmcnt(3)
	v_mfma_f32_32x32x16_bf16 v[32:47], v[240:243], v[236:239], v[32:47]
	ds_read_b128 v[240:243], v209 offset:4672
	s_waitcnt lgkmcnt(3)
	v_mfma_f32_32x32x16_bf16 v[16:31], v[244:247], v[236:239], v[16:31]
	ds_read_b128 v[244:247], v209 offset:9280
	s_waitcnt lgkmcnt(3)
	v_mfma_f32_32x32x16_bf16 v[0:15], v[248:251], v[236:239], v[0:15]
	ds_read_b128 v[248:251], v209 offset:13888
	v_cvt_pk_bf16_f32 v236, v112, v113
	v_cvt_pk_bf16_f32 v237, v114, v115
	v_cvt_pk_bf16_f32 v238, v116, v117
	v_cvt_pk_bf16_f32 v239, v118, v119
	s_waitcnt lgkmcnt(3)
	s_nop 0
	v_mfma_f32_32x32x16_bf16 v[48:63], v[222:225], v[236:239], v[48:63]
	ds_read_b128 v[222:225], v209 offset:96
	s_waitcnt lgkmcnt(3)
	v_mfma_f32_32x32x16_bf16 v[32:47], v[240:243], v[236:239], v[32:47]
	ds_read_b128 v[240:243], v209 offset:4704
	s_waitcnt lgkmcnt(3)
	v_mfma_f32_32x32x16_bf16 v[16:31], v[244:247], v[236:239], v[16:31]
	ds_read_b128 v[244:247], v209 offset:9312
	s_waitcnt lgkmcnt(3)
	v_mfma_f32_32x32x16_bf16 v[0:15], v[248:251], v[236:239], v[0:15]
	ds_read_b128 v[248:251], v209 offset:13920
	v_cvt_pk_bf16_f32 v236, v120, v121
	v_cvt_pk_bf16_f32 v237, v122, v123
	v_cvt_pk_bf16_f32 v238, v124, v125
	v_cvt_pk_bf16_f32 v239, v126, v127
	s_waitcnt lgkmcnt(3)
	s_nop 0
	v_mfma_f32_32x32x16_bf16 v[48:63], v[222:225], v[236:239], v[48:63]
	s_waitcnt lgkmcnt(2)
	v_mfma_f32_32x32x16_bf16 v[32:47], v[240:243], v[236:239], v[32:47]
	s_waitcnt lgkmcnt(1)
	v_mfma_f32_32x32x16_bf16 v[16:31], v[244:247], v[236:239], v[16:31]
	s_waitcnt lgkmcnt(0)
	v_mfma_f32_32x32x16_bf16 v[0:15], v[248:251], v[236:239], v[0:15]
	s_setprio 0
	v_mov_b32_e32 v170, v234
	v_mov_b32_e32 v215, v162

.Lda_upd0:
	v_max_f32_e32 v234, v170, v162
	v_cmp_le_f32_e64 vcc, |v234|, s98
	s_nop 1
	v_cndmask_b32_e64 v234, v234, 0, vcc
	v_cmp_neq_f32_e32 vcc, 0, v234
	s_or_b64 s[100:101], s[100:101], vcc
	v_sub_f32_e32 v162, v170, v234
	v_exp_f32_e32 v170, v162
	s_nop 0
	v_pk_mul_f32 v[62:63], v[62:63], v[170:171] op_sel_hi:[1,0]
	v_pk_mul_f32 v[60:61], v[60:61], v[170:171] op_sel_hi:[1,0]
	v_pk_mul_f32 v[58:59], v[58:59], v[170:171] op_sel_hi:[1,0]
	v_pk_mul_f32 v[56:57], v[56:57], v[170:171] op_sel_hi:[1,0]
	v_pk_mul_f32 v[54:55], v[54:55], v[170:171] op_sel_hi:[1,0]
	v_pk_mul_f32 v[52:53], v[52:53], v[170:171] op_sel_hi:[1,0]
	v_pk_mul_f32 v[50:51], v[50:51], v[170:171] op_sel_hi:[1,0]
	v_pk_mul_f32 v[48:49], v[48:49], v[170:171] op_sel_hi:[1,0]
	v_pk_mul_f32 v[46:47], v[46:47], v[170:171] op_sel_hi:[1,0]
	v_pk_mul_f32 v[44:45], v[44:45], v[170:171] op_sel_hi:[1,0]
	v_pk_mul_f32 v[42:43], v[42:43], v[170:171] op_sel_hi:[1,0]
	v_pk_mul_f32 v[40:41], v[40:41], v[170:171] op_sel_hi:[1,0]
	v_pk_mul_f32 v[38:39], v[38:39], v[170:171] op_sel_hi:[1,0]
	v_pk_mul_f32 v[36:37], v[36:37], v[170:171] op_sel_hi:[1,0]
	v_pk_mul_f32 v[34:35], v[34:35], v[170:171] op_sel_hi:[1,0]
	v_pk_mul_f32 v[32:33], v[32:33], v[170:171] op_sel_hi:[1,0]
	v_pk_mul_f32 v[30:31], v[30:31], v[170:171] op_sel_hi:[1,0]
	v_pk_mul_f32 v[28:29], v[28:29], v[170:171] op_sel_hi:[1,0]
	v_pk_mul_f32 v[26:27], v[26:27], v[170:171] op_sel_hi:[1,0]
	v_pk_mul_f32 v[24:25], v[24:25], v[170:171] op_sel_hi:[1,0]
	v_pk_mul_f32 v[22:23], v[22:23], v[170:171] op_sel_hi:[1,0]
	v_pk_mul_f32 v[20:21], v[20:21], v[170:171] op_sel_hi:[1,0]
	v_pk_mul_f32 v[18:19], v[18:19], v[170:171] op_sel_hi:[1,0]
	v_pk_mul_f32 v[16:17], v[16:17], v[170:171] op_sel_hi:[1,0]
	v_pk_mul_f32 v[14:15], v[14:15], v[170:171] op_sel_hi:[1,0]
	v_pk_mul_f32 v[12:13], v[12:13], v[170:171] op_sel_hi:[1,0]
	v_pk_mul_f32 v[10:11], v[10:11], v[170:171] op_sel_hi:[1,0]
	v_pk_mul_f32 v[8:9], v[8:9], v[170:171] op_sel_hi:[1,0]
	v_pk_mul_f32 v[6:7], v[6:7], v[170:171] op_sel_hi:[1,0]
	v_pk_mul_f32 v[4:5], v[4:5], v[170:171] op_sel_hi:[1,0]
	v_pk_mul_f32 v[2:3], v[2:3], v[170:171] op_sel_hi:[1,0]
	v_pk_mul_f32 v[0:1], v[0:1], v[170:171] op_sel_hi:[1,0]
.LBB0_212:
	s_cmp_eq_u64 s[100:101], 0
	s_cbranch_scc1 .Lda_nosub1
	v_sub_f32_e32 v71, v71, v234
	v_sub_f32_e32 v70, v70, v234
	v_sub_f32_e32 v69, v69, v234
	v_sub_f32_e32 v68, v68, v234
	v_sub_f32_e32 v67, v67, v234
	v_sub_f32_e32 v66, v66, v234
	v_sub_f32_e32 v65, v65, v234
	v_sub_f32_e32 v64, v64, v234
	v_sub_f32_e32 v87, v87, v234
	v_sub_f32_e32 v86, v86, v234
	v_sub_f32_e32 v85, v85, v234
	v_sub_f32_e32 v84, v84, v234
	v_sub_f32_e32 v83, v83, v234
	v_sub_f32_e32 v82, v82, v234
	v_sub_f32_e32 v81, v81, v234
	v_sub_f32_e32 v80, v80, v234
	v_sub_f32_e32 v75, v75, v234
	v_sub_f32_e32 v74, v74, v234
	v_sub_f32_e32 v73, v73, v234
	v_sub_f32_e32 v72, v72, v234
	v_sub_f32_e32 v91, v91, v234
	v_sub_f32_e32 v90, v90, v234
	v_sub_f32_e32 v89, v89, v234
	v_sub_f32_e32 v88, v88, v234
	v_sub_f32_e32 v79, v79, v234
	v_sub_f32_e32 v78, v78, v234
	v_sub_f32_e32 v77, v77, v234
	v_sub_f32_e32 v76, v76, v234
	v_sub_f32_e32 v95, v95, v234
	v_sub_f32_e32 v94, v94, v234
	v_sub_f32_e32 v93, v93, v234
	v_sub_f32_e32 v92, v92, v234
.Lda_nosub1:
	v_exp_f32_e32 v64, v64
	v_exp_f32_e32 v65, v65
	v_exp_f32_e32 v66, v66
	v_exp_f32_e32 v67, v67
	v_exp_f32_e32 v68, v68
	v_exp_f32_e32 v69, v69
	v_exp_f32_e32 v70, v70
	v_exp_f32_e32 v71, v71
	v_exp_f32_e32 v80, v80
	v_exp_f32_e32 v81, v81
	v_exp_f32_e32 v82, v82
	v_exp_f32_e32 v83, v83
	v_exp_f32_e32 v84, v84
	v_exp_f32_e32 v85, v85
	v_exp_f32_e32 v86, v86
	v_exp_f32_e32 v87, v87
	v_exp_f32_e32 v72, v72
	v_exp_f32_e32 v73, v73
	v_exp_f32_e32 v74, v74
	v_exp_f32_e32 v75, v75
	v_exp_f32_e32 v88, v88
	v_exp_f32_e32 v90, v90
	v_exp_f32_e32 v91, v91
	v_exp_f32_e32 v89, v89
	v_exp_f32_e32 v76, v76
	v_exp_f32_e32 v77, v77
	v_exp_f32_e32 v78, v78
	v_exp_f32_e32 v79, v79
	v_exp_f32_e32 v92, v92
	v_exp_f32_e32 v93, v93
	v_exp_f32_e32 v94, v94
	v_exp_f32_e32 v95, v95
	v_pk_add_f32 v[226:227], v[68:69], v[84:85]
	v_pk_add_f32 v[236:237], v[64:65], v[80:81]
	v_pk_add_f32 v[238:239], v[70:71], v[86:87]
	v_pk_add_f32 v[240:241], v[66:67], v[82:83]
	v_pk_add_f32 v[222:223], v[74:75], v[90:91]
	v_pk_add_f32 v[224:225], v[72:73], v[88:89]
	v_pk_add_f32 v[238:239], v[240:241], v[238:239]
	v_pk_add_f32 v[226:227], v[236:237], v[226:227]
	v_pk_add_f32 v[162:163], v[76:77], v[92:93]
	v_pk_add_f32 v[164:165], v[78:79], v[94:95]
	v_pk_add_f32 v[224:225], v[224:225], v[226:227]
	v_pk_add_f32 v[222:223], v[222:223], v[238:239]
	v_pk_add_f32 v[162:163], v[162:163], v[224:225]
	v_pk_add_f32 v[164:165], v[164:165], v[222:223]
	v_add_f32_e32 v162, v162, v163
	v_add_f32_e32 v163, v164, v165
	v_add_f32_e32 v162, v162, v163
	v_fmac_f32_e32 v162, v215, v170
	s_setprio 1
	v_add_u32_e32 v163, v202, v169
	ds_read_b128 v[222:225], v163 offset:52224
	ds_read_b128 v[240:243], v163 offset:56832
	ds_read_b128 v[244:247], v163 offset:61440
	ds_read_b128 v[248:251], v207 offset:52224
	v_cvt_pk_bf16_f32 v236, v64, v65
	v_cvt_pk_bf16_f32 v237, v66, v67
	v_cvt_pk_bf16_f32 v238, v68, v69
	v_cvt_pk_bf16_f32 v239, v70, v71
	s_waitcnt lgkmcnt(3)
	s_nop 0
	v_mfma_f32_32x32x16_bf16 v[48:63], v[222:225], v[236:239], v[48:63]
	ds_read_b128 v[222:225], v163 offset:52256
	s_waitcnt lgkmcnt(3)
	v_mfma_f32_32x32x16_bf16 v[32:47], v[240:243], v[236:239], v[32:47]
	ds_read_b128 v[240:243], v163 offset:56864
	s_waitcnt lgkmcnt(3)
	v_mfma_f32_32x32x16_bf16 v[16:31], v[244:247], v[236:239], v[16:31]
	ds_read_b128 v[244:247], v163 offset:61472
	s_waitcnt lgkmcnt(3)
	v_mfma_f32_32x32x16_bf16 v[0:15], v[248:251], v[236:239], v[0:15]
	ds_read_b128 v[248:251], v207 offset:52256
	v_cvt_pk_bf16_f32 v236, v72, v73
	v_cvt_pk_bf16_f32 v237, v74, v75
	v_cvt_pk_bf16_f32 v238, v76, v77
	v_cvt_pk_bf16_f32 v239, v78, v79
	s_waitcnt lgkmcnt(3)
	s_nop 0
	v_mfma_f32_32x32x16_bf16 v[48:63], v[222:225], v[236:239], v[48:63]
	ds_read_b128 v[222:225], v163 offset:52288
	s_waitcnt lgkmcnt(3)
	v_mfma_f32_32x32x16_bf16 v[32:47], v[240:243], v[236:239], v[32:47]
	ds_read_b128 v[240:243], v163 offset:56896
	s_waitcnt lgkmcnt(3)
	v_mfma_f32_32x32x16_bf16 v[16:31], v[244:247], v[236:239], v[16:31]
	ds_read_b128 v[244:247], v163 offset:61504
	s_waitcnt lgkmcnt(3)
	v_mfma_f32_32x32x16_bf16 v[0:15], v[248:251], v[236:239], v[0:15]
	ds_read_b128 v[248:251], v207 offset:52288
	v_cvt_pk_bf16_f32 v236, v80, v81
	v_cvt_pk_bf16_f32 v237, v82, v83
	v_cvt_pk_bf16_f32 v238, v84, v85
	v_cvt_pk_bf16_f32 v239, v86, v87
	s_waitcnt lgkmcnt(3)
	s_nop 0
	v_mfma_f32_32x32x16_bf16 v[48:63], v[222:225], v[236:239], v[48:63]
	ds_read_b128 v[222:225], v163 offset:52320
	s_waitcnt lgkmcnt(3)
	v_mfma_f32_32x32x16_bf16 v[32:47], v[240:243], v[236:239], v[32:47]
	ds_read_b128 v[240:243], v163 offset:56928
	s_waitcnt lgkmcnt(3)
	v_mfma_f32_32x32x16_bf16 v[16:31], v[244:247], v[236:239], v[16:31]
	ds_read_b128 v[244:247], v163 offset:61536
	s_waitcnt lgkmcnt(3)
	v_mfma_f32_32x32x16_bf16 v[0:15], v[248:251], v[236:239], v[0:15]
	ds_read_b128 v[248:251], v207 offset:52320
	v_cvt_pk_bf16_f32 v236, v88, v89
	v_cvt_pk_bf16_f32 v237, v90, v91
	v_cvt_pk_bf16_f32 v238, v92, v93
	v_cvt_pk_bf16_f32 v239, v94, v95
	s_waitcnt lgkmcnt(3)
	s_nop 0
	v_mfma_f32_32x32x16_bf16 v[48:63], v[222:225], v[236:239], v[48:63]
	s_waitcnt lgkmcnt(2)
	v_mfma_f32_32x32x16_bf16 v[32:47], v[240:243], v[236:239], v[32:47]
	s_waitcnt lgkmcnt(1)
	v_mfma_f32_32x32x16_bf16 v[16:31], v[244:247], v[236:239], v[16:31]
	s_waitcnt lgkmcnt(0)
	v_mfma_f32_32x32x16_bf16 v[0:15], v[248:251], v[236:239], v[0:15]
	s_setprio 0
	v_mov_b32_e32 v170, v234
	v_mov_b32_e32 v215, v162

.Lda_upd1:
	v_max_f32_e32 v234, v170, v162
	v_cmp_le_f32_e64 vcc, |v234|, s98
	s_nop 1
	v_cndmask_b32_e64 v234, v234, 0, vcc
	v_cmp_neq_f32_e32 vcc, 0, v234
	s_or_b64 s[100:101], s[100:101], vcc
	v_sub_f32_e32 v162, v170, v234
	v_exp_f32_e32 v170, v162
	s_nop 0
	v_pk_mul_f32 v[62:63], v[62:63], v[170:171] op_sel_hi:[1,0]
	v_pk_mul_f32 v[60:61], v[60:61], v[170:171] op_sel_hi:[1,0]
	v_pk_mul_f32 v[58:59], v[58:59], v[170:171] op_sel_hi:[1,0]
	v_pk_mul_f32 v[56:57], v[56:57], v[170:171] op_sel_hi:[1,0]
	v_pk_mul_f32 v[54:55], v[54:55], v[170:171] op_sel_hi:[1,0]
	v_pk_mul_f32 v[52:53], v[52:53], v[170:171] op_sel_hi:[1,0]
	v_pk_mul_f32 v[50:51], v[50:51], v[170:171] op_sel_hi:[1,0]
	v_pk_mul_f32 v[48:49], v[48:49], v[170:171] op_sel_hi:[1,0]
	v_pk_mul_f32 v[46:47], v[46:47], v[170:171] op_sel_hi:[1,0]
	v_pk_mul_f32 v[44:45], v[44:45], v[170:171] op_sel_hi:[1,0]
	v_pk_mul_f32 v[42:43], v[42:43], v[170:171] op_sel_hi:[1,0]
	v_pk_mul_f32 v[40:41], v[40:41], v[170:171] op_sel_hi:[1,0]
	v_pk_mul_f32 v[38:39], v[38:39], v[170:171] op_sel_hi:[1,0]
	v_pk_mul_f32 v[36:37], v[36:37], v[170:171] op_sel_hi:[1,0]
	v_pk_mul_f32 v[34:35], v[34:35], v[170:171] op_sel_hi:[1,0]
	v_pk_mul_f32 v[32:33], v[32:33], v[170:171] op_sel_hi:[1,0]
	v_pk_mul_f32 v[30:31], v[30:31], v[170:171] op_sel_hi:[1,0]
	v_pk_mul_f32 v[28:29], v[28:29], v[170:171] op_sel_hi:[1,0]
	v_pk_mul_f32 v[26:27], v[26:27], v[170:171] op_sel_hi:[1,0]
	v_pk_mul_f32 v[24:25], v[24:25], v[170:171] op_sel_hi:[1,0]
	v_pk_mul_f32 v[22:23], v[22:23], v[170:171] op_sel_hi:[1,0]
	v_pk_mul_f32 v[20:21], v[20:21], v[170:171] op_sel_hi:[1,0]
	v_pk_mul_f32 v[18:19], v[18:19], v[170:171] op_sel_hi:[1,0]
	v_pk_mul_f32 v[16:17], v[16:17], v[170:171] op_sel_hi:[1,0]
	v_pk_mul_f32 v[14:15], v[14:15], v[170:171] op_sel_hi:[1,0]
	v_pk_mul_f32 v[12:13], v[12:13], v[170:171] op_sel_hi:[1,0]
	v_pk_mul_f32 v[10:11], v[10:11], v[170:171] op_sel_hi:[1,0]
	v_pk_mul_f32 v[8:9], v[8:9], v[170:171] op_sel_hi:[1,0]
	v_pk_mul_f32 v[6:7], v[6:7], v[170:171] op_sel_hi:[1,0]
	v_pk_mul_f32 v[4:5], v[4:5], v[170:171] op_sel_hi:[1,0]
	v_pk_mul_f32 v[2:3], v[2:3], v[170:171] op_sel_hi:[1,0]
	v_pk_mul_f32 v[0:1], v[0:1], v[170:171] op_sel_hi:[1,0]
	s_branch .LBB0_203
